# mixer D unmasked sub-steps hand re-scheduled: K and V LDS fragment reads issued up front (renamed registers), row-max tree, exp2 arguments via independent temporaries
# speedup vs baseline: 1.1457x; 1.0119x over previous
; DI unsigned cvtpk(float lo, float hi) { f32x2_t v = {lo, hi}; bf16x2_t b = __builtin_convertvector(v, bf16x2_t); return __builtin_bit_cast(unsigned, b); }
; template <int DVB, bool MASKED = true>
; DI void attn_step32(const bf16* Kt, int KP, const bf16* Vt, int VP, const bf16x8 (&qf)[4], f32x16 (&o)[DVB], float& m, float& l, unsigned vmask, float c2, int lane) {
;   const int r32 = lane & 31, h = lane >> 5;
;   f32x16 s;
; #pragma unroll
;   for (int i = 0; i < 16; ++i) s[i] = 0.f;
; #pragma unroll
;   for (int t = 0; t < 4; ++t) { const bf16x8 kf = *(const bf16x8*)(Kt + r32 * KP + t * 16 + h * 8); s = mfma32(kf, qf[t], s); }
;   float mx = -INFINITY;
; #pragma unroll
;   for (int i = 0; i < 16; ++i) { if (MASKED) { s[i] = ((vmask >> i) & 1u) ? s[i] : -INFINITY; } mx = fmaxf(mx, s[i]); }
;   mx = half_max(mx);
;   const float mxs = mx * c2;
;   if (__any(mxs > m + 6.f)) {
;     const float mn = fmaxf(m, mxs);
;     const float alpha = fexp2(m - mn); l *= alpha;
; #pragma unroll
;     for (int d = 0; d < DVB; ++d)
; #pragma unroll
;       for (int i = 0; i < 16; ++i) o[d][i] *= alpha;
;     m = mn;
;   }
;   float ps = 0.f; const float negm = -m;
; #pragma unroll
;   for (int i = 0; i < 16; ++i) { const float pv = fexp2(__builtin_fmaf(s[i], c2, negm)); s[i] = pv; ps += pv; }
;   l += ps;
;   bf16x8 pf[2];
;   { u32x4 a, b; a.x = cvtpk(s[0], s[1]); a.y = cvtpk(s[2], s[3]); a.z = cvtpk(s[4], s[5]); a.w = cvtpk(s[6], s[7]);
;     b.x = cvtpk(s[8], s[9]); b.y = cvtpk(s[10], s[11]); b.z = cvtpk(s[12], s[13]); b.w = cvtpk(s[14], s[15]);
;     pf[0] = __builtin_bit_cast(bf16x8, a); pf[1] = __builtin_bit_cast(bf16x8, b); }
;   const int i16 = lane & 15, q = i16 >> 2, pp = i16 & 3, blk = (lane >> 4) & 1;
; #pragma unroll
;   for (int d = 0; d < DVB; ++d)
; #pragma unroll
;     for (int sk = 0; sk < 2; ++sk) {
;       const s16x4 lo = trread(Vt + (16 * sk + 4 * h + q) * VP + 32 * d + 16 * blk + 4 * pp);
;       const s16x4 hi = trread(Vt + (16 * sk + 8 + 4 * h + q) * VP + 32 * d + 16 * blk + 4 * pp);
;       const bf16x8 vf = __builtin_shufflevector(lo, hi, 0, 1, 2, 3, 4, 5, 6, 7);
;       o[d] = mfma32(vf, pf[sk], o[d]);
;     }
; DI void mixerD_unit(const Params& p, int b, int head, int qb, char* lds) {
;     ...
;           attn_step32<4, false>(Ks + sub * 32 * DKP, DKP, Vs + sub * 32 * DVP, DVP, qf, o, m, l, 0xffffu, 0.125f * LOG2E, lane);
.LBB0_2588:
	s_add_i32 s1, s0, 0x2400
	v_mov_b32_e32 v66, s1
	v_mov_b32_e32 v67, s0
	v_cndmask_b32_e64 v66, v66, v67, s[6:7]
	s_sub_i32 s1, s65, 32
	v_add3_u32 v155, v66, v131, v152
	v_add_u32_e32 v153, s0, v148
	v_cmp_le_i32_e32 vcc, s1, v125
	s_and_saveexec_b64 s[0:1], vcc
	s_cbranch_execz .LBB0_2598
	s_add_i32 s2, s65, -1
	v_cmp_le_i32_e32 vcc, s2, v65
	v_add_f32_e32 v163, 0x40c00000, v154
	s_and_saveexec_b64 s[2:3], vcc
	s_xor_b64 s[2:3], exec, s[2:3]
	s_cbranch_execz .LBB0_2593
	ds_read_b128 v[66:69], v155
	ds_read_b128 v[156:159], v155 offset:32
	ds_read_b128 v[200:203], v155 offset:64
	ds_read_b128 v[164:167], v155 offset:96
	s_waitcnt lgkmcnt(3)
	v_mfma_f32_32x32x16_bf16 v[66:81], v[66:69], v[90:93], 0
	s_waitcnt lgkmcnt(2)
	v_mfma_f32_32x32x16_bf16 v[66:81], v[156:159], v[82:85], v[66:81]
	s_waitcnt lgkmcnt(1)
	v_mfma_f32_32x32x16_bf16 v[66:81], v[200:203], v[86:89], v[66:81]
	s_waitcnt lgkmcnt(0)
	v_mfma_f32_32x32x16_bf16 v[66:81], v[164:167], v[94:97], v[66:81]
	v_lshlrev_b32_e32 v216, 1, v133
	v_lshlrev_b32_e32 v217, 1, v147
	v_add3_u32 v218, v153, v216, v217
	v_add_f32_e32 v240, 0x40c00000, v154
	ds_read_b64_tr_b16 v[204:205], v218 offset:18432
	ds_read_b64_tr_b16 v[206:207], v218 offset:20608
	ds_read_b64_tr_b16 v[208:209], v218 offset:22784
	ds_read_b64_tr_b16 v[210:211], v218 offset:24960
	ds_read_b64_tr_b16 v[156:157], v218 offset:18496
	ds_read_b64_tr_b16 v[160:161], v218 offset:18560
	ds_read_b64_tr_b16 v[164:165], v218 offset:18624
	ds_read_b64_tr_b16 v[158:159], v218 offset:20672
	ds_read_b64_tr_b16 v[162:163], v218 offset:20736
	ds_read_b64_tr_b16 v[166:167], v218 offset:20800
	ds_read_b64_tr_b16 v[212:213], v218 offset:22848
	ds_read_b64_tr_b16 v[168:169], v218 offset:22912
	ds_read_b64_tr_b16 v[172:173], v218 offset:22976
	ds_read_b64_tr_b16 v[214:215], v218 offset:25024
	ds_read_b64_tr_b16 v[170:171], v218 offset:25088
	ds_read_b64_tr_b16 v[174:175], v218 offset:25152
	v_max3_f32 v219, v66, v67, v68
	v_max3_f32 v220, v69, v70, v71
	v_max3_f32 v221, v72, v73, v74
	v_max3_f32 v222, v75, v76, v77
	v_max3_f32 v223, v78, v79, v80
	v_max3_f32 v219, v219, v220, v221
	v_max3_f32 v222, v222, v223, v81
	v_max3_f32 v219, v219, v222, s56
	v_mov_b32_e32 v220, v219
	s_nop 1
	v_permlane32_swap_b32_e32 v219, v220
	v_max_f32_e32 v219, v219, v220
	v_mul_f32_e32 v219, 0x3e38aa3b, v219
	v_cmp_gt_f32_e32 vcc, v219, v240
	s_cbranch_vccz .Ld_norescale_u0
	v_max_f32_e32 v220, v154, v219
	v_sub_f32_e32 v154, v154, v220
	v_exp_f32_e32 v154, v154
	s_nop 0
	v_mul_f32_e32 v64, v64, v154
	v_pk_mul_f32 v[62:63], v[62:63], v[154:155] op_sel_hi:[1,0]
	v_pk_mul_f32 v[60:61], v[60:61], v[154:155] op_sel_hi:[1,0]
	v_pk_mul_f32 v[58:59], v[58:59], v[154:155] op_sel_hi:[1,0]
	v_pk_mul_f32 v[56:57], v[56:57], v[154:155] op_sel_hi:[1,0]
	v_pk_mul_f32 v[54:55], v[54:55], v[154:155] op_sel_hi:[1,0]
	v_pk_mul_f32 v[52:53], v[52:53], v[154:155] op_sel_hi:[1,0]
	v_pk_mul_f32 v[50:51], v[50:51], v[154:155] op_sel_hi:[1,0]
	v_pk_mul_f32 v[48:49], v[48:49], v[154:155] op_sel_hi:[1,0]
	v_pk_mul_f32 v[46:47], v[46:47], v[154:155] op_sel_hi:[1,0]
	v_pk_mul_f32 v[44:45], v[44:45], v[154:155] op_sel_hi:[1,0]
	v_pk_mul_f32 v[42:43], v[42:43], v[154:155] op_sel_hi:[1,0]
	v_pk_mul_f32 v[40:41], v[40:41], v[154:155] op_sel_hi:[1,0]
	v_pk_mul_f32 v[38:39], v[38:39], v[154:155] op_sel_hi:[1,0]
	v_pk_mul_f32 v[36:37], v[36:37], v[154:155] op_sel_hi:[1,0]
	v_pk_mul_f32 v[34:35], v[34:35], v[154:155] op_sel_hi:[1,0]
	v_pk_mul_f32 v[32:33], v[32:33], v[154:155] op_sel_hi:[1,0]
	v_pk_mul_f32 v[30:31], v[30:31], v[154:155] op_sel_hi:[1,0]
	v_pk_mul_f32 v[28:29], v[28:29], v[154:155] op_sel_hi:[1,0]
	v_pk_mul_f32 v[26:27], v[26:27], v[154:155] op_sel_hi:[1,0]
	v_pk_mul_f32 v[24:25], v[24:25], v[154:155] op_sel_hi:[1,0]
	v_pk_mul_f32 v[22:23], v[22:23], v[154:155] op_sel_hi:[1,0]
	v_pk_mul_f32 v[20:21], v[20:21], v[154:155] op_sel_hi:[1,0]
	v_pk_mul_f32 v[18:19], v[18:19], v[154:155] op_sel_hi:[1,0]
	v_pk_mul_f32 v[16:17], v[16:17], v[154:155] op_sel_hi:[1,0]
	v_pk_mul_f32 v[14:15], v[14:15], v[154:155] op_sel_hi:[1,0]
	v_pk_mul_f32 v[12:13], v[12:13], v[154:155] op_sel_hi:[1,0]
	v_pk_mul_f32 v[10:11], v[10:11], v[154:155] op_sel_hi:[1,0]
	v_pk_mul_f32 v[8:9], v[8:9], v[154:155] op_sel_hi:[1,0]
	v_pk_mul_f32 v[6:7], v[6:7], v[154:155] op_sel_hi:[1,0]
	v_pk_mul_f32 v[4:5], v[4:5], v[154:155] op_sel_hi:[1,0]
	v_pk_mul_f32 v[2:3], v[2:3], v[154:155] op_sel_hi:[1,0]
	v_pk_mul_f32 v[0:1], v[0:1], v[154:155] op_sel_hi:[1,0]
	v_mov_b32_e32 v154, v220
.Ld_norescale_u0:
	v_fma_f32 v224, v66, s57, -v154
	v_fma_f32 v225, v67, s57, -v154
	v_fma_f32 v226, v68, s57, -v154
	v_fma_f32 v227, v69, s57, -v154
	v_fma_f32 v228, v70, s57, -v154
	v_fma_f32 v229, v71, s57, -v154
	v_fma_f32 v230, v72, s57, -v154
	v_fma_f32 v231, v73, s57, -v154
	v_fma_f32 v232, v74, s57, -v154
	v_fma_f32 v233, v75, s57, -v154
	v_fma_f32 v234, v76, s57, -v154
	v_fma_f32 v235, v77, s57, -v154
	v_fma_f32 v236, v78, s57, -v154
	v_fma_f32 v237, v79, s57, -v154
	v_fma_f32 v238, v80, s57, -v154
	v_fma_f32 v239, v81, s57, -v154
	v_exp_f32_e32 v176, v224
	v_exp_f32_e32 v177, v225
	v_exp_f32_e32 v178, v226
	v_exp_f32_e32 v179, v227
	v_exp_f32_e32 v180, v228
	v_exp_f32_e32 v181, v229
	v_exp_f32_e32 v184, v230
	v_exp_f32_e32 v185, v231
	v_exp_f32_e32 v186, v232
	v_exp_f32_e32 v187, v233
	v_exp_f32_e32 v188, v234
	v_exp_f32_e32 v189, v235
	v_exp_f32_e32 v190, v236
	v_exp_f32_e32 v191, v237
	v_exp_f32_e32 v192, v238
	v_exp_f32_e32 v193, v239
	v_cvt_pk_bf16_f32 v66, v176, v177
	v_cvt_pk_bf16_f32 v67, v178, v179
	v_cvt_pk_bf16_f32 v68, v180, v181
	v_cvt_pk_bf16_f32 v69, v184, v185
	v_cvt_pk_bf16_f32 v70, v186, v187
	v_cvt_pk_bf16_f32 v71, v188, v189
	v_cvt_pk_bf16_f32 v72, v190, v191
	v_cvt_pk_bf16_f32 v73, v192, v193
	v_add_f32_e32 v74, v176, v177
	v_add_f32_e32 v75, v186, v187
	s_waitcnt lgkmcnt(0)
	v_mfma_f32_32x32x16_bf16 v[32:47], v[156:159], v[66:69], v[32:47]
	v_add_f32_e32 v74, v178, v74
	v_add_f32_e32 v75, v188, v75
	v_mfma_f32_32x32x16_bf16 v[48:63], v[204:207], v[66:69], v[48:63]
	v_add_f32_e32 v74, v179, v74
	v_add_f32_e32 v75, v189, v75
	v_mfma_f32_32x32x16_bf16 v[32:47], v[212:215], v[70:73], v[32:47]
	v_add_f32_e32 v74, v180, v74
	v_add_f32_e32 v75, v190, v75
	v_mfma_f32_32x32x16_bf16 v[16:31], v[160:163], v[66:69], v[16:31]
	v_add_f32_e32 v74, v181, v74
	v_add_f32_e32 v75, v191, v75
	v_mfma_f32_32x32x16_bf16 v[0:15], v[164:167], v[66:69], v[0:15]
	v_add_f32_e32 v74, v184, v74
	v_add_f32_e32 v75, v192, v75
	v_mfma_f32_32x32x16_bf16 v[48:63], v[208:211], v[70:73], v[48:63]
	v_add_f32_e32 v74, v185, v74
	v_add_f32_e32 v75, v193, v75
	v_mfma_f32_32x32x16_bf16 v[16:31], v[168:171], v[70:73], v[16:31]
	v_add_f32_e32 v74, v74, v75
	v_add_f32_e32 v64, v64, v74
	v_mfma_f32_32x32x16_bf16 v[0:15], v[172:175], v[70:73], v[0:15]

; DI float fexp2(float x) { return __builtin_amdgcn_exp2f(x); }
; DI f32x16 mfma32(bf16x8 a, bf16x8 b, f32x16 c) { return __builtin_amdgcn_mfma_f32_32x32x16_bf16(a, b, c, 0, 0, 0); }
; DI float half_max(float v) { auto rr = __builtin_amdgcn_permlane32_swap(__float_as_uint(v), __float_as_uint(v), false, false); return fmaxf(__uint_as_float(rr[0]), __uint_as_float(rr[1])); }
; template <int DVB, bool MASKED = true>
; DI void attn_step32(const bf16* Kt, int KP, const bf16* Vt, int VP, const bf16x8 (&qf)[4], f32x16 (&o)[DVB], float& m, float& l, unsigned vmask, float c2, int lane) {
;   const int r32 = lane & 31, h = lane >> 5;
;   f32x16 s;
; #pragma unroll
;   for (int i = 0; i < 16; ++i) s[i] = 0.f;
; #pragma unroll
;   for (int t = 0; t < 4; ++t) { const bf16x8 kf = *(const bf16x8*)(Kt + r32 * KP + t * 16 + h * 8); s = mfma32(kf, qf[t], s); }
;   float mx = -INFINITY;
; #pragma unroll
;   for (int i = 0; i < 16; ++i) { if (MASKED) { s[i] = ((vmask >> i) & 1u) ? s[i] : -INFINITY; } mx = fmaxf(mx, s[i]); }
;   mx = half_max(mx);
;   const float mxs = mx * c2;
;   if (__any(mxs > m + 6.f)) {
;     const float mn = fmaxf(m, mxs);
;     const float alpha = fexp2(m - mn); l *= alpha;
; #pragma unroll
;     for (int d = 0; d < DVB; ++d)
; #pragma unroll
;       for (int i = 0; i < 16; ++i) o[d][i] *= alpha;
;     m = mn;
;   }
; DI void mixerD_unit(const Params& p, int b, int head, int qb, char* lds) {
;     ...
;           attn_step32<4, false>(Ks + sub * 32 * DKP, DKP, Vs + sub * 32 * DVP, DVP, qf, o, m, l, 0xffffu, 0.125f * LOG2E, lane);
.LBB0_2598:
	s_or_b64 exec, exec, s[0:1]
	v_cmp_le_i32_e32 vcc, s65, v125
	s_and_saveexec_b64 s[0:1], vcc
	s_cbranch_execz .LBB0_2585
	s_add_i32 s2, s65, 31
	v_cmp_le_i32_e32 vcc, s2, v65
	v_add_f32_e32 v162, 0x40c00000, v154
	s_and_saveexec_b64 s[2:3], vcc
	s_xor_b64 s[2:3], exec, s[2:3]
	s_cbranch_execz .LBB0_2603
	ds_read_b128 v[66:69], v155 offset:4608
	ds_read_b128 v[156:159], v155 offset:4640
	ds_read_b128 v[200:203], v155 offset:4672
	ds_read_b128 v[164:167], v155 offset:4704
	s_waitcnt lgkmcnt(3)
	v_mfma_f32_32x32x16_bf16 v[66:81], v[66:69], v[90:93], 0
	s_waitcnt lgkmcnt(2)
	v_mfma_f32_32x32x16_bf16 v[66:81], v[156:159], v[82:85], v[66:81]
	s_waitcnt lgkmcnt(1)
	v_mfma_f32_32x32x16_bf16 v[66:81], v[200:203], v[86:89], v[66:81]
	s_waitcnt lgkmcnt(0)
	v_mfma_f32_32x32x16_bf16 v[66:81], v[164:167], v[94:97], v[66:81]
	v_lshlrev_b32_e32 v216, 1, v133
	v_lshlrev_b32_e32 v217, 1, v147
	v_add3_u32 v218, v153, v216, v217
	v_add_f32_e32 v240, 0x40c00000, v154
	ds_read_b64_tr_b16 v[204:205], v218 offset:27136
	ds_read_b64_tr_b16 v[206:207], v218 offset:29312
	ds_read_b64_tr_b16 v[208:209], v218 offset:31488
	ds_read_b64_tr_b16 v[210:211], v218 offset:33664
	ds_read_b64_tr_b16 v[156:157], v218 offset:27200
	ds_read_b64_tr_b16 v[160:161], v218 offset:27264
	ds_read_b64_tr_b16 v[164:165], v218 offset:27328
	ds_read_b64_tr_b16 v[158:159], v218 offset:29376
	ds_read_b64_tr_b16 v[162:163], v218 offset:29440
	ds_read_b64_tr_b16 v[166:167], v218 offset:29504
	ds_read_b64_tr_b16 v[212:213], v218 offset:31552
	ds_read_b64_tr_b16 v[168:169], v218 offset:31616
	ds_read_b64_tr_b16 v[172:173], v218 offset:31680
	ds_read_b64_tr_b16 v[214:215], v218 offset:33728
	ds_read_b64_tr_b16 v[170:171], v218 offset:33792
	ds_read_b64_tr_b16 v[174:175], v218 offset:33856
	v_max3_f32 v219, v66, v67, v68
	v_max3_f32 v220, v69, v70, v71
	v_max3_f32 v221, v72, v73, v74
	v_max3_f32 v222, v75, v76, v77
	v_max3_f32 v223, v78, v79, v80
	v_max3_f32 v219, v219, v220, v221
	v_max3_f32 v222, v222, v223, v81
	v_max3_f32 v219, v219, v222, s56
	v_mov_b32_e32 v220, v219
	s_nop 1
	v_permlane32_swap_b32_e32 v219, v220
	v_max_f32_e32 v219, v219, v220
	v_mul_f32_e32 v219, 0x3e38aa3b, v219
	v_cmp_gt_f32_e32 vcc, v219, v240
	s_cbranch_vccz .Ld_norescale_u1
	v_max_f32_e32 v220, v154, v219
	v_sub_f32_e32 v154, v154, v220
	v_exp_f32_e32 v154, v154
	s_nop 0
	v_mul_f32_e32 v64, v64, v154
	v_pk_mul_f32 v[62:63], v[62:63], v[154:155] op_sel_hi:[1,0]
	v_pk_mul_f32 v[60:61], v[60:61], v[154:155] op_sel_hi:[1,0]
	v_pk_mul_f32 v[58:59], v[58:59], v[154:155] op_sel_hi:[1,0]
	v_pk_mul_f32 v[56:57], v[56:57], v[154:155] op_sel_hi:[1,0]
	v_pk_mul_f32 v[54:55], v[54:55], v[154:155] op_sel_hi:[1,0]
	v_pk_mul_f32 v[52:53], v[52:53], v[154:155] op_sel_hi:[1,0]
	v_pk_mul_f32 v[50:51], v[50:51], v[154:155] op_sel_hi:[1,0]
	v_pk_mul_f32 v[48:49], v[48:49], v[154:155] op_sel_hi:[1,0]
	v_pk_mul_f32 v[46:47], v[46:47], v[154:155] op_sel_hi:[1,0]
	v_pk_mul_f32 v[44:45], v[44:45], v[154:155] op_sel_hi:[1,0]
	v_pk_mul_f32 v[42:43], v[42:43], v[154:155] op_sel_hi:[1,0]
	v_pk_mul_f32 v[40:41], v[40:41], v[154:155] op_sel_hi:[1,0]
	v_pk_mul_f32 v[38:39], v[38:39], v[154:155] op_sel_hi:[1,0]
	v_pk_mul_f32 v[36:37], v[36:37], v[154:155] op_sel_hi:[1,0]
	v_pk_mul_f32 v[34:35], v[34:35], v[154:155] op_sel_hi:[1,0]
	v_pk_mul_f32 v[32:33], v[32:33], v[154:155] op_sel_hi:[1,0]
	v_pk_mul_f32 v[30:31], v[30:31], v[154:155] op_sel_hi:[1,0]
	v_pk_mul_f32 v[28:29], v[28:29], v[154:155] op_sel_hi:[1,0]
	v_pk_mul_f32 v[26:27], v[26:27], v[154:155] op_sel_hi:[1,0]
	v_pk_mul_f32 v[24:25], v[24:25], v[154:155] op_sel_hi:[1,0]
	v_pk_mul_f32 v[22:23], v[22:23], v[154:155] op_sel_hi:[1,0]
	v_pk_mul_f32 v[20:21], v[20:21], v[154:155] op_sel_hi:[1,0]
	v_pk_mul_f32 v[18:19], v[18:19], v[154:155] op_sel_hi:[1,0]
	v_pk_mul_f32 v[16:17], v[16:17], v[154:155] op_sel_hi:[1,0]
	v_pk_mul_f32 v[14:15], v[14:15], v[154:155] op_sel_hi:[1,0]
	v_pk_mul_f32 v[12:13], v[12:13], v[154:155] op_sel_hi:[1,0]
	v_pk_mul_f32 v[10:11], v[10:11], v[154:155] op_sel_hi:[1,0]
	v_pk_mul_f32 v[8:9], v[8:9], v[154:155] op_sel_hi:[1,0]
	v_pk_mul_f32 v[6:7], v[6:7], v[154:155] op_sel_hi:[1,0]
	v_pk_mul_f32 v[4:5], v[4:5], v[154:155] op_sel_hi:[1,0]
	v_pk_mul_f32 v[2:3], v[2:3], v[154:155] op_sel_hi:[1,0]
	v_pk_mul_f32 v[0:1], v[0:1], v[154:155] op_sel_hi:[1,0]
	v_mov_b32_e32 v154, v220
